# RWKV block-loop heads aligned to 64 bytes (code placement)
# baseline (speedup 1.0000x reference)
; #define RW_LANDED(WN, XN, KN, VN) asm volatile("s_waitcnt lgkmcnt(0)" : "+v"(WN), "+v"(XN), "+v"(KN), "+v"(VN) :: "memory")
; template <int DIR>
; DEVINL void rwkv_scan_dir(const Params& p, int task, int lane, int wave) {
;     ...
;   RW_READ(0, WvA, XA, KrA, vhA, 23);
;   RW_LANDED(WvA, XA, KrA, vhA);
.Lrw_ready_d0p:
	ds_read_b64 v[24:25], v6 offset:16
	ds_read_b128 v[26:29], v6 offset:272
	ds_read_b128 v[30:33], v6 offset:528
	ds_read_u16 v34, v7 offset:16
	ds_read_b64 v[36:37], v6 offset:1040
	ds_read_b128 v[38:41], v6 offset:1296
	ds_read_b128 v[42:45], v6 offset:1552
	ds_read_u16 v46, v7 offset:1040
	s_waitcnt lgkmcnt(0)
	.p2alignl 6, 3212836864

; #define RW_LANDED(WN, XN, KN, VN) asm volatile("s_waitcnt lgkmcnt(0)" : "+v"(WN), "+v"(XN), "+v"(KN), "+v"(VN) :: "memory")
; template <int DIR>
; DEVINL void rwkv_scan_dir(const Params& p, int task, int lane, int wave) {
;     ...
;   RW_READ(0, WvA, XA, KrA, vhA, 23);
;   RW_LANDED(WvA, XA, KrA, vhA);
.Lrw_ready_d1p:
	ds_read_b64 v[24:25], v6 offset:15384
	ds_read_b128 v[26:29], v6 offset:15632
	ds_read_b128 v[30:33], v6 offset:15888
	ds_read_u16 v34, v7 offset:15376
	ds_read_b64 v[36:37], v6 offset:14360
	ds_read_b128 v[38:41], v6 offset:14608
	ds_read_b128 v[42:45], v6 offset:14864
	ds_read_u16 v46, v7 offset:14352
	s_waitcnt lgkmcnt(0)
	.p2alignl 6, 3212836864
